# DeltaNet two-step recurrence loop rewritten by hand (114 instead of ~130 VALU ops per iteration, immediate LDS offsets, all-lane output writes)
# baseline (speedup 1.0000x reference)
; __device__ __forceinline__ void dn_task(const Params& p, int l, int task, char* smem) {
;     ...
;     {
;       float4 k0A[2], k1A[2], q0A[2], q1A[2], abA, dtA; float2 vvA;
;       float4 k0B[2], k1B[2], q0B[2], q1B[2], abB, dtB; float2 vvB;
;       DN_LD2(0, k0A, k1A, q0A, q1A, abA, vvA, dtA);
; #pragma unroll 1
;       for (int pp = 0; pp < 16; pp += 2) {
;         DN_LD2(pp + 1, k0B, k1B, q0B, q1B, abB, vvB, dtB);
;         DN_PAIR(pp, k0A, k1A, q0A, q1A, abA, vvA, dtA);
;         const int p2 = (pp + 2 < 16) ? pp + 2 : 15;
;         DN_LD2(p2, k0A, k1A, q0A, q1A, abA, vvA, dtA);
;         DN_PAIR(pp + 1, k0B, k1B, q0B, q1B, abB, vvB, dtB);
;       }
.LBB0_211:
	s_or_b64 exec, exec, s[60:61]
	v_lshl_add_u32 v0, v164, 2, v0
	ds_read_b128 v[10:13], v211 offset:8704
	ds_read_b128 v[14:17], v211 offset:8720
	ds_read_b128 v[18:21], v211 offset:8736
	ds_read_b128 v[22:25], v211 offset:8752
	ds_read2_b32 v[26:27], v0 offset1:1
	ds_read2_b32 v[42:43], v0 offset0:2 offset1:3
	ds_read2_b32 v[44:45], v0 offset0:4 offset1:5
	ds_read2_b32 v[46:47], v0 offset0:6 offset1:7
	ds_read2_b32 v[48:49], v0 offset0:8 offset1:9
	ds_read2_b32 v[50:51], v0 offset0:10 offset1:11
	ds_read2_b32 v[52:53], v0 offset0:12 offset1:13
	ds_read2_b32 v[54:55], v0 offset0:14 offset1:15
	s_waitcnt lgkmcnt(0)
	v_fma_f32 v26, v26, v10, 0
	v_fmac_f32_e32 v26, v27, v11
	v_fmac_f32_e32 v26, v42, v12
	v_fmac_f32_e32 v26, v43, v13
	v_fmac_f32_e32 v26, v44, v14
	v_fmac_f32_e32 v26, v45, v15
	v_fmac_f32_e32 v26, v46, v16
	v_fmac_f32_e32 v26, v47, v17
	v_fmac_f32_e32 v26, v48, v18
	v_fmac_f32_e32 v26, v49, v19
	v_fmac_f32_e32 v26, v50, v20
	v_fmac_f32_e32 v26, v51, v21
	v_fmac_f32_e32 v26, v52, v22
	v_fmac_f32_e32 v26, v53, v23
	v_fmac_f32_e32 v26, v54, v24
	v_fmac_f32_e32 v26, v55, v25
	s_nop 1
	v_add_f32_dpp v0, v26, v26 quad_perm:[1,0,3,2] row_mask:0xf bank_mask:0xf bound_ctrl:1
	s_nop 1
	v_mov_b32_dpp v10, v0 quad_perm:[2,3,0,1] row_mask:0xf bank_mask:0xf bound_ctrl:1
	s_and_saveexec_b64 s[60:61], s[54:55]
	v_add_f32_e32 v0, v0, v10
	ds_write_b32 v197, v0 offset:25856
	s_or_b64 exec, exec, s[60:61]
	s_waitcnt lgkmcnt(0)
	s_barrier
	v_mov_b32_e32 v246, v166
	v_mov_b32_e32 v247, v167
	v_mov_b32_e32 v248, 0x6000
	v_mov_b32_e32 v135, 0
	ds_read_b128 v[26:29], v246 offset:0
	ds_read_b128 v[30:33], v246 offset:16
	ds_read_b128 v[34:37], v246 offset:272
	ds_read_b128 v[38:41], v246 offset:288
	ds_read_b128 v[10:13], v246 offset:8704
	ds_read_b128 v[14:17], v246 offset:8720
	ds_read_b128 v[18:21], v246 offset:8976
	ds_read_b128 v[22:25], v246 offset:8992
	ds_read2_b64 v[42:45], v248 offset0:128 offset1:144
	ds_read2st64_b32 v[50:51], v247 offset0:68 offset1:69
	ds_read_b128 v[46:49], v135 offset:25856
	s_mov_b32 s70, 0
.Ldnp_it:
	s_waitcnt lgkmcnt(0)
	ds_read_b128 v[68:71], v246 offset:544
	ds_read_b128 v[72:75], v246 offset:560
	ds_read_b128 v[76:79], v246 offset:816
	ds_read_b128 v[80:83], v246 offset:832
	ds_read_b128 v[52:55], v246 offset:9248
	ds_read_b128 v[56:59], v246 offset:9264
	ds_read_b128 v[60:63], v246 offset:9520
	ds_read_b128 v[64:67], v246 offset:9536
	ds_read2_b64 v[84:87], v248 offset0:129 offset1:145
	ds_read2st64_b32 v[156:157], v247 offset0:70 offset1:71
	ds_read_b128 v[222:225], v135 offset:25872
	v_pk_mul_f32 v[226:227], v[10:11], v[2:3]
	v_pk_mul_f32 v[228:229], v[18:19], v[2:3]
	v_pk_mul_f32 v[230:231], v[26:27], v[2:3]
	v_pk_mul_f32 v[232:233], v[34:35], v[2:3]
	v_pk_fma_f32 v[226:227], v[12:13], v[4:5], v[226:227]
	v_pk_fma_f32 v[228:229], v[20:21], v[4:5], v[228:229]
	v_pk_fma_f32 v[230:231], v[28:29], v[4:5], v[230:231]
	v_pk_fma_f32 v[232:233], v[36:37], v[4:5], v[232:233]
	v_pk_fma_f32 v[226:227], v[14:15], v[6:7], v[226:227]
	v_pk_fma_f32 v[228:229], v[22:23], v[6:7], v[228:229]
	v_pk_fma_f32 v[230:231], v[30:31], v[6:7], v[230:231]
	v_pk_fma_f32 v[232:233], v[38:39], v[6:7], v[232:233]
	v_pk_fma_f32 v[226:227], v[16:17], v[8:9], v[226:227]
	v_pk_fma_f32 v[228:229], v[24:25], v[8:9], v[228:229]
	v_pk_fma_f32 v[230:231], v[32:33], v[8:9], v[230:231]
	v_pk_fma_f32 v[232:233], v[40:41], v[8:9], v[232:233]
	v_add_f32_e32 v226, v226, v227
	v_add_f32_e32 v228, v228, v229
	v_add_f32_e32 v230, v230, v231
	v_add_f32_e32 v232, v232, v233
	v_add_f32_dpp v226, v226, v226 quad_perm:[1,0,3,2] row_mask:0xf bank_mask:0xf
	v_add_f32_dpp v228, v228, v228 quad_perm:[1,0,3,2] row_mask:0xf bank_mask:0xf
	v_add_f32_dpp v230, v230, v230 quad_perm:[1,0,3,2] row_mask:0xf bank_mask:0xf
	v_add_f32_dpp v232, v232, v232 quad_perm:[1,0,3,2] row_mask:0xf bank_mask:0xf
	v_add_f32_dpp v226, v226, v226 quad_perm:[2,3,0,1] row_mask:0xf bank_mask:0xf
	v_add_f32_dpp v228, v228, v228 quad_perm:[2,3,0,1] row_mask:0xf bank_mask:0xf
	v_add_f32_dpp v230, v230, v230 quad_perm:[2,3,0,1] row_mask:0xf bank_mask:0xf
	v_add_f32_dpp v232, v232, v232 quad_perm:[2,3,0,1] row_mask:0xf bank_mask:0xf
	v_add_f32_dpp v226, v226, v226 row_half_mirror row_mask:0xf bank_mask:0xf
	v_add_f32_dpp v228, v228, v228 row_half_mirror row_mask:0xf bank_mask:0xf
	v_add_f32_dpp v230, v230, v230 row_half_mirror row_mask:0xf bank_mask:0xf
	v_add_f32_dpp v232, v232, v232 row_half_mirror row_mask:0xf bank_mask:0xf
	v_fma_f32 v234, -v42, v226, v50
	v_mul_f32_e32 v241, v42, v228
	v_mul_f32_e32 v238, v42, v43
	v_mul_f32_e32 v234, v44, v234
	v_mul_f32_e32 v237, v42, v230
	v_mul_f32_e32 v239, v238, v232
	v_fma_f32 v235, v46, v234, v241
	v_mul_f32_e32 v240, v43, v234
	v_fma_f32 v237, v47, v234, v237
	v_fma_f32 v236, -v43, v235, v51
	v_fma_f32 v239, v48, v240, v239
	v_mul_f32_e32 v236, v45, v236
	v_fma_f32 v239, v49, v236, v239
	v_pk_mul_f32 v[244:245], v[10:11], v[240:241] op_sel_hi:[1,0]
	v_pk_mul_f32 v[226:227], v[12:13], v[240:241] op_sel_hi:[1,0]
	v_pk_mul_f32 v[228:229], v[14:15], v[240:241] op_sel_hi:[1,0]
	v_pk_mul_f32 v[230:231], v[16:17], v[240:241] op_sel_hi:[1,0]
	v_pk_fma_f32 v[244:245], v[18:19], v[236:237], v[244:245] op_sel_hi:[1,0,1]
	v_pk_fma_f32 v[226:227], v[20:21], v[236:237], v[226:227] op_sel_hi:[1,0,1]
	v_pk_fma_f32 v[228:229], v[22:23], v[236:237], v[228:229] op_sel_hi:[1,0,1]
	v_pk_fma_f32 v[230:231], v[24:25], v[236:237], v[230:231] op_sel_hi:[1,0,1]
	v_pk_fma_f32 v[2:3], v[238:239], v[2:3], v[244:245] op_sel_hi:[0,1,1]
	v_pk_fma_f32 v[4:5], v[238:239], v[4:5], v[226:227] op_sel_hi:[0,1,1]
	v_pk_fma_f32 v[6:7], v[238:239], v[6:7], v[228:229] op_sel_hi:[0,1,1]
	v_pk_fma_f32 v[8:9], v[238:239], v[8:9], v[230:231] op_sel_hi:[0,1,1]
	ds_write2st64_b32 v247, v237, v239 offset0:68 offset1:69
	s_waitcnt lgkmcnt(0)
; __device__ __forceinline__ void dn_task(const Params& p, int l, int task, char* smem) {
;     ...
;     {
;       float4 k0A[2], k1A[2], q0A[2], q1A[2], abA, dtA; float2 vvA;
;       float4 k0B[2], k1B[2], q0B[2], q1B[2], abB, dtB; float2 vvB;
;       DN_LD2(0, k0A, k1A, q0A, q1A, abA, vvA, dtA);
; #pragma unroll 1
;       for (int pp = 0; pp < 16; pp += 2) {
;         DN_LD2(pp + 1, k0B, k1B, q0B, q1B, abB, vvB, dtB);
;         DN_PAIR(pp, k0A, k1A, q0A, q1A, abA, vvA, dtA);
;         const int p2 = (pp + 2 < 16) ? pp + 2 : 15;
;         DN_LD2(p2, k0A, k1A, q0A, q1A, abA, vvA, dtA);
;         DN_PAIR(pp + 1, k0B, k1B, q0B, q1B, abB, vvB, dtB);
;       }
	ds_read_b128 v[26:29], v246 offset:1088
	ds_read_b128 v[30:33], v246 offset:1104
	ds_read_b128 v[34:37], v246 offset:1360
	ds_read_b128 v[38:41], v246 offset:1376
	ds_read_b128 v[10:13], v246 offset:9792
	ds_read_b128 v[14:17], v246 offset:9808
	ds_read_b128 v[18:21], v246 offset:10064
	ds_read_b128 v[22:25], v246 offset:10080
	ds_read2_b64 v[42:45], v248 offset0:130 offset1:146
	ds_read2st64_b32 v[50:51], v247 offset0:72 offset1:73
	ds_read_b128 v[46:49], v135 offset:25888
	v_pk_mul_f32 v[226:227], v[52:53], v[2:3]
	v_pk_mul_f32 v[228:229], v[60:61], v[2:3]
	v_pk_mul_f32 v[230:231], v[68:69], v[2:3]
	v_pk_mul_f32 v[232:233], v[76:77], v[2:3]
	v_pk_fma_f32 v[226:227], v[54:55], v[4:5], v[226:227]
	v_pk_fma_f32 v[228:229], v[62:63], v[4:5], v[228:229]
	v_pk_fma_f32 v[230:231], v[70:71], v[4:5], v[230:231]
	v_pk_fma_f32 v[232:233], v[78:79], v[4:5], v[232:233]
	v_pk_fma_f32 v[226:227], v[56:57], v[6:7], v[226:227]
	v_pk_fma_f32 v[228:229], v[64:65], v[6:7], v[228:229]
	v_pk_fma_f32 v[230:231], v[72:73], v[6:7], v[230:231]
	v_pk_fma_f32 v[232:233], v[80:81], v[6:7], v[232:233]
	v_pk_fma_f32 v[226:227], v[58:59], v[8:9], v[226:227]
	v_pk_fma_f32 v[228:229], v[66:67], v[8:9], v[228:229]
	v_pk_fma_f32 v[230:231], v[74:75], v[8:9], v[230:231]
	v_pk_fma_f32 v[232:233], v[82:83], v[8:9], v[232:233]
	v_add_f32_e32 v226, v226, v227
	v_add_f32_e32 v228, v228, v229
	v_add_f32_e32 v230, v230, v231
	v_add_f32_e32 v232, v232, v233
	v_add_f32_dpp v226, v226, v226 quad_perm:[1,0,3,2] row_mask:0xf bank_mask:0xf
	v_add_f32_dpp v228, v228, v228 quad_perm:[1,0,3,2] row_mask:0xf bank_mask:0xf
	v_add_f32_dpp v230, v230, v230 quad_perm:[1,0,3,2] row_mask:0xf bank_mask:0xf
	v_add_f32_dpp v232, v232, v232 quad_perm:[1,0,3,2] row_mask:0xf bank_mask:0xf
	v_add_f32_dpp v226, v226, v226 quad_perm:[2,3,0,1] row_mask:0xf bank_mask:0xf
	v_add_f32_dpp v228, v228, v228 quad_perm:[2,3,0,1] row_mask:0xf bank_mask:0xf
	v_add_f32_dpp v230, v230, v230 quad_perm:[2,3,0,1] row_mask:0xf bank_mask:0xf
	v_add_f32_dpp v232, v232, v232 quad_perm:[2,3,0,1] row_mask:0xf bank_mask:0xf
	v_add_f32_dpp v226, v226, v226 row_half_mirror row_mask:0xf bank_mask:0xf
	v_add_f32_dpp v228, v228, v228 row_half_mirror row_mask:0xf bank_mask:0xf
	v_add_f32_dpp v230, v230, v230 row_half_mirror row_mask:0xf bank_mask:0xf
	v_add_f32_dpp v232, v232, v232 row_half_mirror row_mask:0xf bank_mask:0xf
	v_fma_f32 v234, -v84, v226, v156
	v_mul_f32_e32 v241, v84, v228
	v_mul_f32_e32 v238, v84, v85
	v_mul_f32_e32 v234, v86, v234
	v_mul_f32_e32 v237, v84, v230
	v_mul_f32_e32 v239, v238, v232
	v_fma_f32 v235, v222, v234, v241
	v_mul_f32_e32 v240, v85, v234
	v_fma_f32 v237, v223, v234, v237
	v_fma_f32 v236, -v85, v235, v157
	v_fma_f32 v239, v224, v240, v239
	v_mul_f32_e32 v236, v87, v236
	v_fma_f32 v239, v225, v236, v239
	v_pk_mul_f32 v[244:245], v[52:53], v[240:241] op_sel_hi:[1,0]
	v_pk_mul_f32 v[226:227], v[54:55], v[240:241] op_sel_hi:[1,0]
	v_pk_mul_f32 v[228:229], v[56:57], v[240:241] op_sel_hi:[1,0]
	v_pk_mul_f32 v[230:231], v[58:59], v[240:241] op_sel_hi:[1,0]
	v_pk_fma_f32 v[244:245], v[60:61], v[236:237], v[244:245] op_sel_hi:[1,0,1]
	v_pk_fma_f32 v[226:227], v[62:63], v[236:237], v[226:227] op_sel_hi:[1,0,1]
	v_pk_fma_f32 v[228:229], v[64:65], v[236:237], v[228:229] op_sel_hi:[1,0,1]
	v_pk_fma_f32 v[230:231], v[66:67], v[236:237], v[230:231] op_sel_hi:[1,0,1]
	v_pk_fma_f32 v[2:3], v[238:239], v[2:3], v[244:245] op_sel_hi:[0,1,1]
	v_pk_fma_f32 v[4:5], v[238:239], v[4:5], v[226:227] op_sel_hi:[0,1,1]
	v_pk_fma_f32 v[6:7], v[238:239], v[6:7], v[228:229] op_sel_hi:[0,1,1]
	v_pk_fma_f32 v[8:9], v[238:239], v[8:9], v[230:231] op_sel_hi:[0,1,1]
	ds_write2st64_b32 v247, v237, v239 offset0:70 offset1:71
	v_add_u32_e32 v246, 0x440, v246
	v_add_u32_e32 v247, 0x400, v247
	v_add_u32_e32 v248, 16, v248
	v_add_u32_e32 v135, 32, v135
	s_add_i32 s70, s70, 1
	s_cmp_lt_u32 s70, 8
	s_cbranch_scc1 .Ldnp_it
	s_waitcnt lgkmcnt(0)
	s_branch .LBB0_192
